# P2: odd workgroups run their retention chunk-state units before their dilated-attention units (on top of the P0 rotation)
# speedup vs baseline: 1.0011x; 1.0011x over previous
.LBB0_478:
	v_readlane_b32 s4, v254, 9
	s_cmp_lt_i32 s4, 3
	s_cselect_b64 s[2:3], -1, 0
	s_and_b64 s[0:1], s[2:3], s[0:1]
	s_andn2_b64 vcc, exec, s[0:1]
	v_readlane_b32 s5, v254, 10
	v_readlane_b32 s6, v254, 11
	v_readlane_b32 s7, v254, 12
	s_cbranch_vccnz .LBB0_515
	v_writelane_b32 v254, s0, 33
	s_waitcnt lgkmcnt(0)
	s_add_u32 s78, s96, 0x5500000
	s_addc_u32 s79, s97, 0
	v_writelane_b32 v254, s1, 34
	v_writelane_b32 v254, s89, 35
	s_mov_b32 s0, s88
	s_mov_b64 s[20:21], s[90:91]
	v_writelane_b32 v254, s0, 36
	s_cmpk_gt_i32 s88, 0x5ff
	s_nop 0
	v_writelane_b32 v254, s1, 37
	s_cbranch_scc1 .LBB0_511
	s_mov_b32 s99, 0
	s_bitcmp1_b32 s88, 0
	s_cbranch_scc0 .Ldil_start
	s_mov_b32 s99, 1
	s_branch .LBB0_511
.Ldil_start:
	v_lshlrev_b32_e32 v0, 2, v227
	global_load_dword v8, v0, s[74:75]
	global_load_dword v9, v0, s[76:77]
	s_waitcnt vmcnt(0) lgkmcnt(0)
	v_and_b32_e32 v8, 0x7fffffff, v8
	v_and_b32_e32 v9, 0x7fffffff, v9
	s_nop 1
	v_max_f32_dpp v8, v8, v8 quad_perm:[1,0,3,2] row_mask:0xf bank_mask:0xf
	v_max_f32_dpp v9, v9, v9 quad_perm:[1,0,3,2] row_mask:0xf bank_mask:0xf
	s_nop 1
	v_max_f32_dpp v8, v8, v8 quad_perm:[2,3,0,1] row_mask:0xf bank_mask:0xf
	v_max_f32_dpp v9, v9, v9 quad_perm:[2,3,0,1] row_mask:0xf bank_mask:0xf
	s_nop 1
	v_max_f32_dpp v8, v8, v8 row_half_mirror row_mask:0xf bank_mask:0xf
	v_max_f32_dpp v9, v9, v9 row_half_mirror row_mask:0xf bank_mask:0xf
	s_nop 1
	v_max_f32_dpp v8, v8, v8 row_mirror row_mask:0xf bank_mask:0xf
	v_max_f32_dpp v9, v9, v9 row_mirror row_mask:0xf bank_mask:0xf
	s_nop 1
	v_readlane_b32 s0, v8, 0
	v_readlane_b32 s1, v8, 16
	v_readlane_b32 s2, v8, 32
	v_readlane_b32 s3, v8, 48
	s_max_u32 s0, s0, s1
	s_max_u32 s2, s2, s3
	s_max_u32 s0, s0, s2
	v_readlane_b32 s1, v9, 0
	v_readlane_b32 s2, v9, 16
	v_readlane_b32 s3, v9, 32
	v_readlane_b32 s98, v9, 48
	s_max_u32 s1, s1, s2
	s_max_u32 s3, s3, s98
	s_max_u32 s1, s1, s3
	s_nop 0
	v_mov_b32_e32 v8, s0
	v_mov_b32_e32 v9, s1
	v_readlane_b32 s0, v254, 36
	v_readlane_b32 s1, v254, 37
	s_mov_b32 s2, s0
	s_mul_hi_i32 s0, s0, 0x55555556
	s_lshr_b32 s1, s0, 31
	s_add_i32 s0, s0, s1
	s_mul_i32 s1, s0, 3
	s_sub_i32 s76, s2, s1
	s_ashr_i32 s94, s0, 7
	s_bfe_u32 s92, s0, 0x30004
	s_and_b32 s0, s0, 15
	s_lshl_b32 s8, s76, 1
	s_lshr_b32 s93, s0, s8
	s_lshl_b32 s1, -1, s8
	s_lshl_b32 s14, s93, 8
	s_ashr_i32 s95, s94, 31
	v_lshlrev_b32_e32 v0, 3, v226
	s_andn2_b32 s77, s0, s1
	s_lshl_b64 s[0:1], s[94:95], 12
	s_add_i32 s15, s14, 0xffffff80
	v_and_b32_e32 v0, 56, v0
	v_mov_b32_e32 v96, 0
	s_mov_b32 s9, 0
	s_cmp_eq_u32 s93, 0
	v_lshlrev_b32_e32 v180, 1, v0
	s_cbranch_scc1 .LBB0_484
	v_lshrrev_b32_e32 v0, 3, v226
	v_or_b32_e32 v0, s15, v0
	v_mov_b32_e32 v1, v96
	v_lshlrev_b64 v[0:1], s8, v[0:1]
	s_or_b32 s2, s0, s77
	s_mov_b32 s3, s1
	v_lshl_add_u64 v[0:1], s[2:3], 0, v[0:1]
	s_movk_i32 s4, 0x1800
	v_mov_b64_e32 v[2:3], s[78:79]
	v_mad_u64_u32 v[2:3], s[2:3], v0, s4, v[2:3]
	v_mov_b32_e32 v0, v3
	v_mad_u64_u32 v[0:1], s[2:3], v1, s4, v[0:1]
	v_mov_b32_e32 v3, v0
	s_lshl_b32 s2, s92, 7
	s_mov_b32 s3, s9
	v_lshl_add_u64 v[0:1], v[2:3], 0, s[2:3]
	v_mov_b32_e32 v181, v96
	v_lshl_add_u64 v[0:1], v[0:1], 0, v[180:181]
	v_add_co_u32_e32 v0, vcc, 0x1000, v0
	s_nop 1
	v_addc_co_u32_e32 v1, vcc, 0, v1, vcc
	global_load_dwordx4 v[96:99], v[0:1], off
	global_load_dwordx4 v[100:103], v[0:1], off offset:1024
	s_branch .LBB0_485

.LBB0_511:
	v_readlane_b32 s88, v254, 36
	v_readlane_b32 s89, v254, 37
	v_readlane_b32 s0, v254, 33
	s_cmpk_gt_i32 s88, 0x1ff
	v_readlane_b32 s89, v254, 35
	s_mov_b64 s[90:91], s[20:21]
	v_readlane_b32 s1, v254, 34
	s_cbranch_scc1 .LBB0_515
	s_cmp_eq_u32 s99, 2
	s_cbranch_scc1 .LBB0_515
	v_lshlrev_b32_e32 v4, 2, v226
	v_lshlrev_b32_e32 v5, 4, v226
	v_readlane_b32 s2, v254, 5
	v_and_b32_e32 v12, 16, v226
	v_and_b32_e32 v6, 48, v5
	v_and_b32_e32 v7, 0xfc0, v4
	v_add_u32_e32 v8, 0x800, v4
	v_add_u32_e32 v9, 0x1800, v4
	s_lshr_b32 s0, s2, 7
	v_and_b32_e32 v5, 0xc0, v5
	v_and_or_b32 v4, v4, 12, v12
	v_lshrrev_b32_e32 v12, 5, v227
	s_bfe_u32 s2, s2, 0x10006
	s_lshl_b32 s3, s0, 13
	v_lshl_or_b32 v5, v12, 9, v5
	s_lshl_b32 s5, s2, 13
	v_lshl_or_b32 v4, v4, 1, v5
	s_add_i32 s3, s3, 0
	v_add_u32_e32 v23, s3, v4
	s_add_i32 s3, s5, 0
	v_add_u32_e32 v3, 0x200, v226
	s_add_i32 s3, s3, 0x8000
	v_lshlrev_b32_e32 v1, 3, v226
	v_add_u32_e32 v2, 0x600, v226
	v_lshrrev_b32_e32 v26, 3, v3
	v_add_u32_e32 v25, s3, v4
	v_lshlrev_b32_e32 v4, 8, v12
	v_and_b32_e32 v0, 0x78, v1
	v_lshrrev_b32_e32 v16, 4, v2
	v_and_b32_e32 v2, 56, v1
	v_lshlrev_b32_e32 v1, 11, v226
	v_sub_u32_e32 v10, 0x7f, v26
	v_and_b32_e32 v11, 31, v226
	v_lshl_or_b32 v4, s0, 11, v4
	s_lshl_b32 s0, s2, 5
	v_lshrrev_b32_e32 v20, 4, v3
	v_lshrrev_b32_e32 v24, 3, v226
	v_and_b32_e32 v3, 0x6000, v1
	v_and_b32_e32 v1, 0x2000, v1
	v_cvt_f32_i32_e32 v21, v10
	v_or3_b32 v4, v4, s0, v11
	v_add3_u32 v3, 0, v3, v6
	v_add3_u32 v1, 0, v1, v6
	v_xor_b32_e32 v6, 0x7f, v24
	v_ashrrev_i32_e32 v5, 31, v4
	v_mov_b32_e32 v17, 0
	v_lshrrev_b32_e32 v18, 4, v226
	v_and_b32_e32 v8, 0x1fc0, v8
	v_and_b32_e32 v9, 0x3fc0, v9
	v_cvt_f32_ubyte0_e32 v19, v6
	v_lshlrev_b32_e32 v6, 6, v24
	v_lshlrev_b32_e32 v10, 6, v26
	v_lshl_add_u64 v[4:5], v[4:5], 1, s[96:97]
	s_mov_b64 s[2:3], 0xe500000
	v_or_b32_e32 v22, 64, v18
	v_mov_b32_e32 v27, v17
	s_mov_b32 s1, 0
	s_movk_i32 s4, 0x1800
	v_add_u32_e32 v36, 0x400, v23
	v_add_u32_e32 v37, 0x400, v25
	v_add_u32_e32 v38, 0x800, v23
	v_add_u32_e32 v39, 0x800, v25
	v_add_u32_e32 v40, 0xc00, v23
	v_add_u32_e32 v41, 0xc00, v25
	v_add_u32_e32 v42, 0x1000, v23
	v_add_u32_e32 v43, 0x1000, v25
	v_add_u32_e32 v44, 0x1400, v23
	v_add_u32_e32 v45, 0x1400, v25
	v_add_u32_e32 v46, 0x1800, v23
	v_add_u32_e32 v47, 0x1800, v25
	v_add_u32_e32 v48, 0x1c00, v23
	v_add_u32_e32 v49, 0x1c00, v25
	v_lshl_add_u64 v[28:29], v[4:5], 0, s[2:3]
	s_lshl_b32 s5, s88, 7
	s_lshl_b32 s6, s90, 7
	v_lshlrev_b32_e32 v30, 1, v0
	v_mov_b32_e32 v50, 0x1800
	v_lshlrev_b32_e32 v32, 1, v2
	v_mov_b32_e32 v33, v17
	v_add_u32_e32 v51, v3, v7
	v_add_u32_e32 v52, v3, v8
	v_add_u32_e32 v53, v3, v9
	v_add_u32_e32 v54, v1, v6
	v_add_u32_e32 v55, v1, v10
	v_mov_b64_e32 v[34:35], s[78:79]
	v_mov_b32_e32 v31, v17
	s_mov_b32 s2, s88
.LBB0_513:
	s_ashr_i32 s8, s2, 7
	s_ashr_i32 s9, s8, 31
	s_bfe_u32 s3, s2, 0x20005
	s_and_b32 s7, s5, 0xf80
	s_lshl_b64 s[8:9], s[8:9], 12
	v_cvt_f32_ubyte0_e32 v0, s3
	s_or_b32 s8, s8, s7
	v_sub_f32_e32 v0, 0xc0a00000, v0
	v_or_b32_e32 v4, s8, v18
	v_exp_f32_e32 v56, v0
	v_or_b32_e32 v6, s8, v20
	v_or_b32_e32 v8, s8, v22
	v_lshl_add_u64 v[0:1], s[8:9], 0, v[16:17]
	v_or_b32_e32 v12, s8, v24
	v_lshl_add_u64 v[2:3], s[8:9], 0, v[26:27]
	v_mad_u64_u32 v[4:5], s[12:13], v4, s4, v[34:35]
	s_mov_b32 s11, s1
	s_lshl_b32 s10, s3, 8
	v_mad_u64_u32 v[6:7], s[12:13], v6, s4, v[34:35]
	v_mad_u64_u32 v[8:9], s[12:13], v8, s4, v[34:35]
	v_mad_u64_u32 v[10:11], s[12:13], v0, s4, v[34:35]
	v_mad_u64_u32 v[12:13], s[12:13], v12, s4, v[34:35]
	v_mad_u64_u32 v[14:15], s[12:13], v2, s4, v[34:35]
	v_mad_i32_i24 v5, s9, v50, v5
	s_lshl_b32 s0, s3, 7
	v_mad_i32_i24 v7, s9, v50, v7
	v_mad_i32_i24 v9, s9, v50, v9
	v_mad_i32_i24 v11, v1, s4, v11
	v_mad_i32_i24 v13, s9, v50, v13
	v_mad_i32_i24 v15, v3, s4, v15
	v_lshl_add_u64 v[0:1], v[4:5], 0, s[10:11]
	v_lshl_add_u64 v[2:3], v[6:7], 0, s[10:11]
	v_lshl_add_u64 v[4:5], v[8:9], 0, s[10:11]
	v_lshl_add_u64 v[6:7], v[10:11], 0, s[10:11]
	v_lshl_add_u64 v[8:9], v[12:13], 0, s[0:1]
	v_lshl_add_u64 v[10:11], v[14:15], 0, s[0:1]
	v_lshl_add_u64 v[64:65], v[0:1], 0, v[30:31]
	v_sub_f32_e32 v76, 1.0, v56
	v_lshl_add_u64 v[66:67], v[2:3], 0, v[30:31]
	v_lshl_add_u64 v[68:69], v[4:5], 0, v[30:31]
	v_lshl_add_u64 v[70:71], v[6:7], 0, v[30:31]
	v_lshl_add_u64 v[72:73], v[8:9], 0, v[32:33]
	v_lshl_add_u64 v[74:75], v[10:11], 0, v[32:33]
	global_load_dwordx4 v[0:3], v[64:65], off offset:1024
	global_load_dwordx4 v[4:7], v[66:67], off offset:1024
	global_load_dwordx4 v[8:11], v[72:73], off offset:512
	global_load_dwordx4 v[12:15], v[74:75], off offset:512
	global_load_dwordx4 v[56:59], v[68:69], off offset:1024
	global_load_dwordx4 v[60:63], v[70:71], off offset:1024
	v_log_f32_e32 v64, v76
	s_ashr_i32 s3, s2, 31
	s_lshl_b64 s[8:9], s[2:3], 14
	s_add_i32 s5, s5, s6
	v_mul_f32_e32 v65, v64, v19
	v_mul_f32_e32 v66, v64, v21
	v_exp_f32_e32 v64, v65
	v_exp_f32_e32 v66, v66
	s_add_i32 s2, s2, s90
	s_cmpk_lt_i32 s2, 0x200
	s_waitcnt vmcnt(5)
	ds_write_b128 v51, v[0:3]
	s_waitcnt vmcnt(4)
	ds_write_b128 v52, v[4:7]
	s_waitcnt vmcnt(1)
	ds_write_b128 v51, v[56:59] offset:4096
	s_waitcnt vmcnt(0)
	ds_write_b128 v53, v[60:63]
	v_lshlrev_b32_e32 v0, 16, v8
	v_and_b32_e32 v1, 0xffff0000, v8
	v_lshlrev_b32_e32 v2, 16, v9
	v_and_b32_e32 v3, 0xffff0000, v9
	v_lshlrev_b32_e32 v4, 16, v10
	v_and_b32_e32 v5, 0xffff0000, v10
	v_lshlrev_b32_e32 v6, 16, v11
	v_and_b32_e32 v7, 0xffff0000, v11
	v_lshlrev_b32_e32 v8, 16, v12
	v_and_b32_e32 v9, 0xffff0000, v12
	v_lshlrev_b32_e32 v10, 16, v13
	v_and_b32_e32 v11, 0xffff0000, v13
	v_lshlrev_b32_e32 v12, 16, v14
	v_and_b32_e32 v13, 0xffff0000, v14
	v_lshlrev_b32_e32 v14, 16, v15
	v_and_b32_e32 v15, 0xffff0000, v15
	v_pk_mul_f32 v[0:1], v[64:65], v[0:1] op_sel_hi:[0,1]
	v_pk_mul_f32 v[2:3], v[64:65], v[2:3] op_sel_hi:[0,1]
	v_pk_mul_f32 v[4:5], v[64:65], v[4:5] op_sel_hi:[0,1]
	v_pk_mul_f32 v[6:7], v[64:65], v[6:7] op_sel_hi:[0,1]
	v_pk_mul_f32 v[8:9], v[66:67], v[8:9] op_sel_hi:[0,1]
	v_pk_mul_f32 v[10:11], v[66:67], v[10:11] op_sel_hi:[0,1]
	v_pk_mul_f32 v[12:13], v[66:67], v[12:13] op_sel_hi:[0,1]
	v_pk_mul_f32 v[14:15], v[66:67], v[14:15] op_sel_hi:[0,1]
	v_cvt_pk_bf16_f32 v0, v0, v1
	v_cvt_pk_bf16_f32 v1, v2, v3
	v_cvt_pk_bf16_f32 v2, v4, v5
	v_cvt_pk_bf16_f32 v3, v6, v7
	v_cvt_pk_bf16_f32 v4, v8, v9
	v_cvt_pk_bf16_f32 v5, v10, v11
	v_cvt_pk_bf16_f32 v6, v12, v13
	v_cvt_pk_bf16_f32 v7, v14, v15
	ds_write_b128 v54, v[0:3] offset:32768
	ds_write_b128 v55, v[4:7] offset:32768
	s_waitcnt lgkmcnt(0)
	s_barrier
	ds_read_b64_tr_b16 v[4:5], v23
	ds_read_b64_tr_b16 v[6:7], v23 offset:256
	ds_read_b64_tr_b16 v[0:1], v25
	ds_read_b64_tr_b16 v[2:3], v25 offset:256
	s_waitcnt lgkmcnt(0)
	ds_read_b64_tr_b16 v[60:61], v36
	ds_read_b64_tr_b16 v[62:63], v36 offset:256
	ds_read_b64_tr_b16 v[56:57], v37
	ds_read_b64_tr_b16 v[58:59], v37 offset:256
	s_waitcnt lgkmcnt(0)
	v_lshl_add_u64 v[64:65], v[28:29], 0, s[8:9]
	v_mfma_f32_32x32x16_bf16 v[0:15], v[4:7], v[0:3], 0
	v_mfma_f32_32x32x16_bf16 v[0:15], v[60:63], v[56:59], v[0:15]
	ds_read_b64_tr_b16 v[60:61], v38
	ds_read_b64_tr_b16 v[62:63], v38 offset:256
	ds_read_b64_tr_b16 v[56:57], v39
	ds_read_b64_tr_b16 v[58:59], v39 offset:256
	s_waitcnt lgkmcnt(0)
	s_nop 0
	v_mfma_f32_32x32x16_bf16 v[0:15], v[60:63], v[56:59], v[0:15]
	ds_read_b64_tr_b16 v[60:61], v40
	ds_read_b64_tr_b16 v[62:63], v40 offset:256
	ds_read_b64_tr_b16 v[56:57], v41
	ds_read_b64_tr_b16 v[58:59], v41 offset:256
	s_waitcnt lgkmcnt(0)
	s_nop 0
	v_mfma_f32_32x32x16_bf16 v[0:15], v[60:63], v[56:59], v[0:15]
	ds_read_b64_tr_b16 v[60:61], v42
	ds_read_b64_tr_b16 v[62:63], v42 offset:256
	ds_read_b64_tr_b16 v[56:57], v43
	ds_read_b64_tr_b16 v[58:59], v43 offset:256
	s_waitcnt lgkmcnt(0)
	s_nop 0
	v_mfma_f32_32x32x16_bf16 v[0:15], v[60:63], v[56:59], v[0:15]
	ds_read_b64_tr_b16 v[60:61], v44
	ds_read_b64_tr_b16 v[62:63], v44 offset:256
	ds_read_b64_tr_b16 v[56:57], v45
	ds_read_b64_tr_b16 v[58:59], v45 offset:256
	s_waitcnt lgkmcnt(0)
	s_nop 0
	v_mfma_f32_32x32x16_bf16 v[0:15], v[60:63], v[56:59], v[0:15]
	ds_read_b64_tr_b16 v[60:61], v46
	ds_read_b64_tr_b16 v[62:63], v46 offset:256
	ds_read_b64_tr_b16 v[56:57], v47
	ds_read_b64_tr_b16 v[58:59], v47 offset:256
	s_waitcnt lgkmcnt(0)
	s_nop 0
	v_mfma_f32_32x32x16_bf16 v[0:15], v[60:63], v[56:59], v[0:15]
	ds_read_b64_tr_b16 v[60:61], v48
	ds_read_b64_tr_b16 v[62:63], v48 offset:256
	ds_read_b64_tr_b16 v[56:57], v49
	ds_read_b64_tr_b16 v[58:59], v49 offset:256
	s_waitcnt lgkmcnt(0)
	s_nop 0
	v_mfma_f32_32x32x16_bf16 v[0:15], v[60:63], v[56:59], v[0:15]
	s_nop 11
	v_cvt_pk_bf16_f32 v0, v0, s0
	v_cvt_pk_bf16_f32 v1, v1, s0
	v_cvt_pk_bf16_f32 v2, v2, s0
	v_cvt_pk_bf16_f32 v3, v3, s0
	v_cvt_pk_bf16_f32 v4, v4, s0
	v_cvt_pk_bf16_f32 v5, v5, s0
	v_cvt_pk_bf16_f32 v6, v6, s0
	v_cvt_pk_bf16_f32 v7, v7, s0
	v_cvt_pk_bf16_f32 v8, v8, s0
	v_cvt_pk_bf16_f32 v9, v9, s0
	v_cvt_pk_bf16_f32 v10, v10, s0
	v_cvt_pk_bf16_f32 v11, v11, s0
	v_cvt_pk_bf16_f32 v12, v12, s0
	v_cvt_pk_bf16_f32 v13, v13, s0
	v_cvt_pk_bf16_f32 v14, v14, s0
	v_cvt_pk_bf16_f32 v15, v15, s0
	global_store_short v[64:65], v0, off
	global_store_short v[64:65], v1, off offset:128
	global_store_short v[64:65], v2, off offset:256
	global_store_short v[64:65], v3, off offset:384
	global_store_short v[64:65], v4, off offset:1024
	global_store_short v[64:65], v5, off offset:1152
	global_store_short v[64:65], v6, off offset:1280
	global_store_short v[64:65], v7, off offset:1408
	global_store_short v[64:65], v8, off offset:2048
	global_store_short v[64:65], v9, off offset:2176
	global_store_short v[64:65], v10, off offset:2304
	global_store_short v[64:65], v11, off offset:2432
	global_store_short v[64:65], v12, off offset:3072
	global_store_short v[64:65], v13, off offset:3200
	global_store_short v[64:65], v14, off offset:3328
	global_store_short v[64:65], v15, off offset:3456
	s_waitcnt lgkmcnt(0)
	s_barrier
	s_cbranch_scc1 .LBB0_513
	v_readlane_b32 s0, v254, 33
	v_readlane_b32 s1, v254, 34
	s_cmp_eq_u32 s99, 1
	s_cbranch_scc0 .LBB0_515
	s_mov_b32 s99, 2
	s_branch .Ldil_start
